# static s_setprio 1 for waves 4-7 at entry of the two attention-style phases (guide 7.4), on top of v75
# baseline (speedup 1.0000x reference)
.LBB0_1000:
	v_readlane_b32 s0, v254, 2
	s_cmp_lt_i32 s0, 5
	s_cselect_b64 s[6:7], -1, 0
	s_and_b64 s[46:47], s[6:7], s[4:5]
	s_andn2_b64 vcc, exec, s[46:47]
	v_readlane_b32 s1, v254, 3
	s_cbranch_vccnz .LBB0_1313
	v_readfirstlane_b32 s43, v0
	s_nop 3
	s_cmpk_ge_u32 s43, 0x100
	s_cbranch_scc0 .Lprio5_done
	s_setprio 1
.Lprio5_done:
	v_bfe_u32 v117, v0, 4, 2
	v_readfirstlane_b32 s43, v0
	s_cmpk_lt_i32 s2, 0x80
	s_waitcnt vmcnt(0)
	v_lshlrev_b32_e32 v57, 3, v206
	v_mov_b32_e32 v91, 0
	v_lshlrev_b32_e32 v90, 3, v117
	v_lshlrev_b32_e32 v58, 2, v117
	v_lshlrev_b32_e32 v42, 2, v206
	s_cbranch_scc1 .LBB0_1003
	v_lshlrev_b32_e32 v2, 2, v117
	v_mov_b32_e32 v3, v91
	v_mov_b32_e32 v207, v91
	v_lshlrev_b32_e32 v220, 2, v206
	s_mov_b64 s[4:5], 0
	v_mov_b64_e32 v[92:93], v[2:3]
	v_mov_b64_e32 v[94:95], v[206:207]
	s_branch .LBB0_1004

.LBB0_1363:
	v_readlane_b32 s0, v254, 2
	s_cmp_lt_i32 s0, 6
	s_cselect_b64 s[6:7], -1, 0
	s_and_b64 s[28:29], s[6:7], s[4:5]
	s_andn2_b64 vcc, exec, s[28:29]
	v_readlane_b32 s1, v254, 3
	s_cbranch_vccnz .LBB0_1918
	v_readfirstlane_b32 s0, v0
	s_nop 3
	s_cmpk_ge_u32 s0, 0x100
	s_cbranch_scc0 .Lprio6_done
	s_setprio 1
.Lprio6_done:
	v_readfirstlane_b32 s0, v0
	s_waitcnt lgkmcnt(0)
	s_and_b32 s3, s2, 31
	s_lshr_b32 s69, s0, 6
	s_lshl_b32 s68, s3, 6
	s_lshl_b32 s0, s3, 8
	s_add_u32 s0, s54, s0
	s_addc_u32 s1, s55, 0
	s_add_u32 s34, s0, 0xc000
	s_addc_u32 s35, s1, 0
	s_and_b32 s70, s2, 1
	v_and_b32_e32 v2, 7, v0
	v_lshlrev_b32_e32 v168, 3, v206
	v_bfe_u32 v165, v0, 2, 4
	s_waitcnt vmcnt(0)
	v_lshl_or_b32 v5, s70, 3, v2
	s_movk_i32 s0, 0x80
	v_mul_u32_u24_e32 v2, 0x110, v165
	v_and_b32_e32 v173, 24, v168
	v_add3_u32 v204, v2, v173, s0
	v_lshlrev_b32_e32 v2, 5, v0
	v_mov_b32_e32 v3, 0
	v_and_b32_e32 v205, 32, v2
	v_lshlrev_b32_e32 v2, 7, v5
	s_lshl_b32 s71, s70, 4
	s_lshl_b32 s72, s70, 6
	v_and_b32_e32 v190, 48, v0
	v_mov_b32_e32 v191, v3
	v_lshl_add_u64 v[6:7], s[54:55], 0, v[2:3]
	v_lshl_add_u64 v[8:9], v[6:7], 0, v[190:191]
	s_mov_b64 s[12:13], 0x1c1c0000
	s_add_u32 s73, s54, 0x4e6aa800
	v_lshlrev_b32_e32 v2, 2, v5
	v_lshl_add_u64 v[178:179], v[8:9], 0, s[12:13]
	s_addc_u32 s74, s55, 0
	v_lshl_add_u64 v[8:9], s[54:55], 0, v[2:3]
	s_mov_b64 s[12:13], 0x1f340000
	v_lshl_add_u64 v[180:181], v[8:9], 0, s[12:13]
	s_add_u32 s12, s54, 0x316a2800
	s_addc_u32 s13, s55, 0
	v_bfe_u32 v11, v0, 1, 5
	s_add_u32 s36, s54, 0x23750000
	v_lshlrev_b32_e32 v2, 2, v11
	s_addc_u32 s37, s55, 0
	v_lshl_add_u64 v[182:183], s[12:13], 0, v[2:3]
	v_lshlrev_b32_e32 v2, 8, v5
	s_add_u32 s12, s12, s72
	v_bfe_u32 v1, v0, 4, 2
	v_lshl_add_u64 v[8:9], s[54:55], 0, v[2:3]
	s_addc_u32 s13, s13, 0
	v_lshlrev_b32_e32 v2, 2, v206
	v_lshlrev_b32_e32 v166, 3, v1
	v_mov_b32_e32 v167, v3
	v_lshl_add_u64 v[186:187], s[12:13], 0, v[2:3]
	v_mbcnt_lo_u32_b32 v2, -1, 0
	v_lshlrev_b32_e32 v4, 4, v206
	v_lshl_add_u64 v[6:7], v[6:7], 0, v[166:167]
	s_mov_b64 s[12:13], 0x31fea800
	v_mov_b32_e32 v5, v3
	v_mbcnt_hi_u32_b32 v2, -1, v2
	v_add_u32_e32 v10, 0, v4
	s_mulk_i32 s69, 0x4700
	v_lshlrev_b32_e32 v164, 2, v1
	v_and_b32_e32 v177, 12, v165
	v_and_b32_e32 v171, 15, v0
	v_bfe_u32 v1, v0, 5, 1
	v_and_b32_e32 v200, 0x80, v168
	v_lshl_add_u64 v[8:9], v[8:9], 0, v[190:191]
	s_mov_b64 s[14:15], 0x2f5a2800
	v_lshl_add_u64 v[188:189], v[6:7], 0, s[12:13]
	v_lshl_add_u64 v[4:5], s[54:55], 0, v[4:5]
	s_mov_b64 s[12:13], 0x4e6be400
	s_lshl_b32 s0, s70, 20
	v_and_or_b32 v2, v2, 64, v11
	s_mov_b32 s31, 0
	v_cmp_eq_u32_e64 s[4:5], 0, v206
	v_bfe_u32 v169, v0, 3, 1
	v_or_b32_e32 v170, 0x200, v168
	v_or_b32_e32 v172, 0x400, v168
	v_or_b32_e32 v174, 0x600, v168
	v_cmp_gt_u32_e64 s[6:7], 32, v206
	v_and_b32_e32 v175, 1, v0
	v_or_b32_e32 v198, 2, v177
	v_or_b32_e32 v199, 3, v165
	v_lshl_or_b32 v176, v171, 2, v200
	v_and_b32_e32 v201, 0x78, v168
	v_mul_u32_u24_e32 v202, 0x110, v1
	v_mul_u32_u24_e32 v203, 0x110, v171
	v_cmp_gt_u32_e64 s[8:9], 16, v206
	v_or_b32_e32 v207, 2, v1
	v_or_b32_e32 v208, 4, v1
	v_or_b32_e32 v209, 6, v1
	v_or_b32_e32 v210, 8, v1
	v_or_b32_e32 v211, 10, v1
	v_or_b32_e32 v212, 12, v1
	v_or_b32_e32 v213, 14, v1
	v_or_b32_e32 v214, 16, v1
	v_or_b32_e32 v215, 18, v1
	v_or_b32_e32 v216, 20, v1
	v_or_b32_e32 v217, 22, v1
	v_or_b32_e32 v218, 24, v1
	v_or_b32_e32 v219, 26, v1
	v_or_b32_e32 v220, 28, v1
	v_or_b32_e32 v221, 30, v1
	v_or_b32_e32 v222, 1, v164
	v_or_b32_e32 v223, 2, v164
	v_or_b32_e32 v224, 3, v164
	v_or_b32_e32 v225, 16, v164
	v_or_b32_e32 v226, 17, v164
	v_or_b32_e32 v227, 18, v164
	v_or_b32_e32 v228, 19, v164
	v_cmp_gt_u32_e64 s[10:11], 8, v171
	v_lshl_add_u64 v[184:185], v[8:9], 0, s[14:15]
	v_lshl_add_u64 v[192:193], v[4:5], 0, s[12:13]
	s_lshl_b32 s75, s0, 1
	s_mov_b32 s76, 0xff800000
	s_movk_i32 s77, 0x1fff
	v_mov_b32_e32 v167, 0x1ff
	v_mov_b32_e32 v191, 0x1fe
	v_mov_b32_e32 v229, 0xff800000
	v_mov_b32_e32 v230, 0x41380000
	v_add_u32_e32 v231, s69, v10
	v_lshlrev_b32_e32 v232, 2, v2
	v_mov_b32_e32 v233, 0xc0
	s_branch .LBB0_1367
